# in-projection: weight rows of a tile staged so a wave's two column pieces are adjacent; epilogue writes whole 128-byte lines (DPP row exchange)
# baseline (speedup 1.0000x reference)
; template <class Epi, class Sched, bool ALIGN_EPI = false, bool SP2 = false>
; __device__ __forceinline__ void gemm_phase(PG8_LAS unsigned char* lds, const Gemm g, const Sched& S, const Epi& E) {
;     const int tid = otid(), wid = __builtin_amdgcn_readfirstlane(tid >> 6), lane = tid & 63, wr = wid >> 2, wc = wid & 3, fr = lane & 15, fq = lane >> 4;
;     const int K = g.K, nt = K / BK;
;     unsigned voffA[2], voffB[2];
; #pragma unroll
;     for (int i = 0; i < 2; ++i) { int R, C; stage_rc(tid * 16 + i * 8192, R, C); const int Rb = Epi::PERM ? ((R & ~31) + perm32(R & 31)) : R;
;         voffA[i] = (unsigned)(R * K + C) * 2u; voffB[i] = (unsigned)(Rb * K + C) * 2u; }
;     const size_t kstep = (size_t)(BK * 2);
;     const size_t hstep = (size_t)HALF * K * 2;
;     const size_t tstep = 2 * hstep;
;     const unsigned ldsw = (unsigned)wid * 1024u;
;     const int aoff = lds_byte(wr * 64 + fr, fq * 8), boff = lds_byte(wc * 32 + fr, fq * 8);
;     ...
;     Unit cur, nxt; int ui = 0;
;     if (!S.next(0, cur)) return;
;     f32x4 acc[2][2][4][2];
; #pragma unroll
;     for (int a = 0; a < 2; ++a)
; #pragma unroll
;         for (int b = 0; b < 2; ++b)
; #pragma unroll
;             for (int m = 0; m < 4; ++m)
; #pragma unroll
;                 for (int n = 0; n < 2; ++n) acc[a][b][m][n] = (f32x4){0.f, 0.f, 0.f, 0.f};
;     bf16x8 At[4][2], B0[2][2], B1[2][2];
;     const char* cA = (const char*)g.A + (size_t)cur.pm * tstep; const char* cB = (const char*)g.Bt + (size_t)cur.pn * tstep;
;     S.a_ready(cur);
;     if constexpr (SP2) {
;         PG8_STAGE(PG8_SB(0, 0), cB, voffB); PG8_STAGE(PG8_SB(0, 1), cB + hstep, voffB); PG8_STAGE(PG8_SA(0, 0), cA, voffA); PG8_STAGE(PG8_SA(0, 1), cA + hstep, voffA);
;         if (wr == 1) PG8_BAR;
;         PG8_WAIT_V(2); PG8_BAR;
;         PG8_STAGE(PG8_SB(1, 0), cB + kstep, voffB); PG8_STAGE(PG8_SA(1, 0), cA + kstep, voffA); PG8_STAGE(PG8_SB(1, 1), cB + hstep + kstep, voffB);
;         PG8_WAIT_V(6); PG8_BAR;
;     } else {
;         PG8_STAGE(PG8_SB(0, 0), cB, voffB); PG8_STAGE(PG8_SA(0, 0), cA, voffA); PG8_STAGE(PG8_SB(0, 1), cB + hstep, voffB); PG8_STAGE(PG8_SA(0, 1), cA + hstep, voffA);
;         if (wr == 1) PG8_BAR;
;         PG8_WAIT_V(4); PG8_BAR;
;         PG8_STAGE(PG8_SB(1, 0), cB + kstep, voffB); PG8_STAGE(PG8_SA(1, 0), cA + kstep, voffA); PG8_STAGE(PG8_SB(1, 1), cB + hstep + kstep, voffB);
.LBB0_550:
	s_andn2_b64 vcc, exec, s[8:9]
	s_cbranch_vccnz .LBB0_582
	v_ashrrev_i32_e32 v0, 31, v10
	v_lshrrev_b32_e32 v0, 26, v0
	v_add_u32_e32 v0, v10, v0
	v_ashrrev_i32_e32 v11, 6, v0
	v_bfe_i32 v0, v10, 27, 1
	s_waitcnt lgkmcnt(0)
	v_lshlrev_b32_e32 v2, 4, v10
	v_lshrrev_b32_e32 v0, 22, v0
	v_add_u32_e32 v0, v2, v0
	v_and_b32_e32 v0, 0xfffffc00, v0
	v_sub_u32_e32 v0, v2, v0
	v_lshrrev_b32_e32 v3, 4, v0
	v_bitop3_b32 v3, v3, v0, 32 bitop3:0x6c
	v_ashrrev_i32_e32 v0, 31, v0
	v_lshrrev_b32_e32 v0, 26, v0
	v_add_u32_e32 v0, v3, v0
	v_ashrrev_i32_e32 v12, 6, v0
	v_lshlrev_b32_e32 v4, 3, v11
	v_mul_i32_i24_e32 v5, 64, v12
	v_and_b32_e32 v4, -16, v4
	v_sub_u32_e32 v3, v3, v5
	v_mov_b32_e32 v7, 1
	v_add_u32_e32 v0, v12, v4
	v_ashrrev_i16_sdwa v3, v7, sext(v3) dst_sel:DWORD dst_unused:UNUSED_PAD src0_sel:DWORD src1_sel:BYTE_0
	v_lshlrev_b32_e32 v4, 5, v11
	v_bfe_i32 v13, v3, 0, 16
	v_lshlrev_b32_e32 v3, 1, v0
	v_lshrrev_b32_e32 v5, 2, v0
	v_and_b32_e32 v6, 3, v12
	s_mov_b32 s4, 0xfffe0
	v_and_b32_e32 v4, 32, v4
	v_and_b32_e32 v3, 24, v3
	v_and_b32_e32 v5, 4, v5
	v_and_or_b32 v6, v0, s4, v6
	v_or3_b32 v3, v6, v5, v3
	v_add_lshl_u32 v4, v4, v13, 1
	v_add_u32_e32 v2, 0x2000, v2
	v_lshl_add_u32 v130, v0, 12, v4
	v_lshl_add_u32 v0, v3, 12, v4
	v_lshrrev_b32_e32 v3, 8, v10
	v_lshl_add_u32 v0, v3, 17, v0
	v_ashrrev_i32_e32 v3, 31, v2
	v_lshrrev_b32_e32 v3, 22, v3
	v_add_u32_e32 v3, v2, v3
	v_ashrrev_i32_e32 v14, 10, v3
	v_mul_i32_i24_e32 v3, 0x400, v14
	v_sub_u32_e32 v2, v2, v3
	v_lshrrev_b32_e32 v3, 4, v2
	v_bitop3_b32 v2, v3, v2, 32 bitop3:0x6c
	v_ashrrev_i32_e32 v4, 31, v2
	v_lshrrev_b32_e32 v4, 26, v4
	v_lshlrev_b32_e32 v3, 3, v14
	v_add_u32_e32 v4, v2, v4
	v_and_b32_e32 v3, -16, v3
	v_ashrrev_i32_e32 v15, 6, v4
	v_add_u32_e32 v3, v15, v3
	v_and_b32_e32 v4, 0xc0, v4
	v_and_b32_e32 v6, 3, v15
	s_ashr_i32 s20, s14, 6
	s_ashr_i32 s43, s42, 31
	s_ashr_i32 s17, s16, 31
	s_ashr_i32 s15, s14, 8
	v_sub_u32_e32 v2, v2, v4
	v_and_or_b32 v6, v3, s4, v6
	s_lshl_b32 s4, s20, 10
	s_lshl_b64 s[6:7], s[42:43], 20
	s_lshl_b64 s[8:9], s[16:17], 20
	v_ashrrev_i16_sdwa v2, v7, sext(v2) dst_sel:DWORD dst_unused:UNUSED_PAD src0_sel:DWORD src1_sel:BYTE_0
	s_add_u32 s10, s96, s8
	v_lshlrev_b32_e32 v5, 5, v14
	v_bfe_i32 v16, v2, 0, 16
	v_lshlrev_b32_e32 v2, 1, v3
	v_lshrrev_b32_e32 v4, 2, v3
	s_addc_u32 s11, s97, s9
	s_add_i32 s5, s4, 0
	v_and_b32_e32 v5, 32, v5
	v_and_b32_e32 v2, 24, v2
	v_and_b32_e32 v4, 4, v4
	s_add_i32 m0, s5, 0x10000
	v_or3_b32 v2, v6, v4, v2
	v_add_lshl_u32 v4, v5, v16, 1
	global_load_lds_dwordx4 v0, s[10:11]
	s_add_i32 m0, s5, 0x12000
	v_lshl_add_u32 v134, v2, 12, v4
	v_lshrrev_b32_e32 v2, 8, v10
	v_lshl_add_u32 v134, v2, 17, v134
	v_add_u32_e32 v134, 0x40000, v134
	s_add_u32 s8, s10, 0x20000
	global_load_lds_dwordx4 v134, s[10:11]
	s_addc_u32 s9, s11, 0
	s_add_i32 m0, s5, 0x14000
	v_lshl_add_u32 v132, v3, 12, v4
	global_load_lds_dwordx4 v0, s[8:9]
	s_add_i32 m0, s5, 0x16000
	s_add_u32 s50, s18, s6
	s_addc_u32 s51, s19, s7
	s_add_i32 s6, s5, 0x2000
	global_load_lds_dwordx4 v134, s[8:9]
	s_mov_b32 m0, s5
	s_add_u32 s8, s50, 0x80000
	global_load_lds_dwordx4 v130, s[50:51]
	s_mov_b32 m0, s6
	s_addc_u32 s9, s51, 0
	s_add_i32 s7, s5, 0x4000
	global_load_lds_dwordx4 v132, s[50:51]
	s_mov_b32 m0, s7
	s_add_i32 s17, s5, 0x6000
	global_load_lds_dwordx4 v130, s[8:9]
	s_mov_b32 m0, s17
	v_mov_b32_e32 v135, v1
	global_load_lds_dwordx4 v132, s[8:9]
	v_mov_b32_e32 v131, v1
	v_mov_b32_e32 v133, v1
	s_cmp_eq_u32 s15, 1
	v_lshl_add_u64 v[8:9], s[10:11], 0, v[0:1]
	v_lshl_add_u64 v[6:7], s[10:11], 0, v[134:135]
	v_lshl_add_u64 v[2:3], s[50:51], 0, v[130:131]
	s_cselect_b64 s[8:9], -1, 0
	s_cmp_lg_u32 s15, 1
	v_lshl_add_u64 v[4:5], s[50:51], 0, v[132:133]
	s_cbranch_scc1 .LBB0_553
	s_barrier
.LBB0_553:
	v_readlane_b32 s12, v254, 48
	v_readlane_b32 s13, v254, 49
	s_mul_i32 s12, s12, 3
	s_ashr_i32 s13, s12, 31
	s_lshl_b64 s[12:13], s[12:13], 18
	v_readlane_b32 s21, v254, 46
	s_add_u32 s12, s21, s12
	v_readlane_b32 s21, v254, 47
	s_addc_u32 s13, s21, s13
	s_lshl_b32 s20, s20, 5
	s_and_b32 s23, s20, 0x60
	s_add_i32 m0, s5, 0x18000
	v_lshl_add_u64 v[8:9], v[8:9], 0, s[34:35]
	s_lshl_b32 s22, s15, 13
	s_lshl_b32 s26, s23, 7
	s_waitcnt vmcnt(2)
	s_barrier
	global_load_lds_dwordx4 v[8:9], off
	v_lshl_add_u64 v[6:7], v[6:7], 0, s[34:35]
	s_add_i32 m0, s5, 0x1a000
	s_add_i32 s30, s5, 0x8000
	s_add_i32 s47, s5, 0xa000
	global_load_lds_dwordx4 v[6:7], off
	v_lshl_add_u64 v[2:3], v[2:3], 0, s[34:35]
	s_mov_b32 m0, s30
	s_add_u32 s20, s10, 0x20080
	global_load_lds_dwordx4 v[2:3], off
	v_lshl_add_u64 v[2:3], v[4:5], 0, s[34:35]
	s_mov_b32 m0, s47
	s_addc_u32 s21, s11, 0
	global_load_lds_dwordx4 v[2:3], off
	s_add_i32 m0, s5, 0x1c000
	v_lshl_add_u64 v[2:3], s[20:21], 0, v[0:1]
	global_load_lds_dwordx4 v[2:3], off
	v_lshl_add_u64 v[2:3], s[20:21], 0, v[134:135]
	s_add_i32 m0, s5, 0x1e000
	s_cmpk_lt_u32 s14, 0x100
	global_load_lds_dwordx4 v[2:3], off
	v_lshrrev_b32_e32 v3, 1, v10
	v_and_b32_e32 v3, 24, v3
	v_and_b32_e32 v2, 15, v10
	v_lshlrev_b32_e32 v4, 1, v3
	v_lshl_or_b32 v147, s15, 6, v2
	v_lshl_or_b32 v2, v2, 6, v4
	v_lshlrev_b32_e32 v4, 2, v10
	v_and_b32_e32 v4, 32, v4
	v_bitop3_b32 v5, v2, s22, v4 bitop3:0xde
	v_bitop3_b32 v149, v2, s26, v4 bitop3:0xde
	v_lshlrev_b32_e32 v2, 15, v11
	v_and_b32_e32 v2, 0xffff0000, v2
	v_or_b32_e32 v150, s23, v3
	v_lshl_add_u32 v2, v12, 12, v2
	v_and_b32_e32 v3, 1, v11
	v_lshl_or_b32 v2, v3, 6, v2
	v_lshl_add_u32 v136, v13, 1, v2
	v_lshlrev_b32_e32 v2, 15, v14
	v_and_b32_e32 v2, 0xffff0000, v2
	s_waitcnt vmcnt(6)
	s_cselect_b64 s[14:15], -1, 0
	s_ashr_i32 s49, s92, 31
	s_ashr_i32 s54, s64, 31
	v_lshl_add_u32 v2, v15, 12, v2
	v_and_b32_e32 v3, 1, v14
	s_cmp_lg_u64 s[74:75], 0
	v_lshl_or_b32 v2, v3, 6, v2
	s_cselect_b64 s[20:21], -1, 0
	v_mov_b32_e32 v137, v1
	v_lshl_add_u32 v138, v16, 1, v2
	v_mov_b32_e32 v139, v1
	s_mov_b32 s55, 0
	v_add_u32_e32 v151, 0, v5
	s_barrier
	s_branch .LBB0_556

; #define PG8_STAGE(bufoff, gbase, voff) do { _Pragma("unroll") for (int _i = 0; _i < 2; ++_i) \
;         __builtin_amdgcn_global_load_lds((const unsigned*)((const char*)(gbase) + (voff)[_i]), (PG8_LAS unsigned*)(lds + (bufoff) + ldsw + _i * 8192), 16, 0, 0); } while (0)
; #define PG8_LDA(dst, b, h) do { _Pragma("unroll") for (int m = 0; m < 4; ++m) _Pragma("unroll") for (int k = 0; k < 2; ++k) dst[m][k] = *(const PG8_LAS bf16x8*)(lds + PG8_SA(b, h) + aoff + m * 2048 + k * 1024); } while (0)
; #define PG8_LDB(dst, b, h) do { _Pragma("unroll") for (int n = 0; n < 2; ++n) _Pragma("unroll") for (int k = 0; k < 2; ++k) dst[n][k] = *(const PG8_LAS bf16x8*)(lds + PG8_SB(b, h) + boff + n * 2048 + k * 1024); } while (0)
; #define PG8_MMA(ai, bj, At, Bt) do { __builtin_amdgcn_s_setprio(1); _Pragma("unroll") for (int m = 0; m < 4; ++m) _Pragma("unroll") for (int n = 0; n < 2; ++n) _Pragma("unroll") for (int k = 0; k < 2; ++k) \
;         acc[ai][bj][m][n] = __builtin_amdgcn_mfma_f32_16x16x32_bf16(Bt[n][k], At[m][k], acc[ai][bj][m][n], 0, 0, 0); __builtin_amdgcn_s_setprio(0); } while (0)
; #define PG8_WAIT_V(n) asm volatile("s_waitcnt vmcnt(" #n ")" ::: "memory")
; #define PG8_WAIT_L(n) asm volatile("s_waitcnt lgkmcnt(" #n ")" ::: "memory")
; #define PG8_BAR __builtin_amdgcn_s_barrier()
; #define PG8_SCHED __builtin_amdgcn_sched_barrier(0)
; template <class Epi, class Sched, bool ALIGN_EPI = false, bool SP2 = false>
; __device__ __forceinline__ void gemm_phase(PG8_LAS unsigned char* lds, const Gemm g, const Sched& S, const Epi& E) {
;     ...
;             PG8_LDB(B0, 0, 0); PG8_LDB(B1, 0, 1); PG8_SCHED; PG8_LDA(At, 0, 0); PG8_STAGE(PG8_SA(1, 1), a1 + hstep, voffA);
;             PG8_WAIT_V(8); PG8_WAIT_L(0); PG8_BAR; PG8_MMA(0, 0, At, B0); PG8_MMA(0, 1, At, B1); PG8_BAR; PG8_SCHED;
;             PG8_LDA(At, 0, 1); PG8_STAGE(PG8_SB(0, 0), b2, voffB); PG8_STAGE(PG8_SB(0, 1), b2 + hstep, voffB); PG8_STAGE(PG8_SA(0, 0), a2, voffA);
;             PG8_WAIT_V(8); PG8_WAIT_L(0); PG8_BAR; PG8_MMA(1, 0, At, B0); PG8_MMA(1, 1, At, B1); PG8_BAR; PG8_SCHED;
.LBB0_559:
	s_add_u32 s10, s50, 0xfff80080
	s_addc_u32 s11, s51, -1
	s_add_i32 s60, 0, 0x10000
	s_cmp_eq_u32 s59, 28
	s_cselect_b32 s53, s37, s11
	s_cselect_b32 s52, s43, s10
	v_add_u32_e32 v144, s60, v149
	s_cselect_b32 s11, s23, s58
	s_cselect_b32 s10, s56, s57
	s_add_i32 s62, 0, 0x14000
	ds_read_b128 v[140:143], v144
	ds_read_b128 v[152:155], v144 offset:1024
	ds_read_b128 v[156:159], v144 offset:2048
	ds_read_b128 v[160:163], v144 offset:3072
	v_add_u32_e32 v144, s62, v149
	ds_read_b128 v[164:167], v144
	ds_read_b128 v[168:171], v144 offset:1024
	ds_read_b128 v[172:175], v144 offset:2048
	ds_read_b128 v[176:179], v144 offset:3072
	v_lshl_add_u64 v[144:145], s[50:51], 0, v[136:137]
	s_add_i32 m0, s5, 0xc000
	ds_read_b128 v[180:183], v151
	ds_read_b128 v[184:187], v151 offset:1024
	ds_read_b128 v[188:191], v151 offset:2048
	ds_read_b128 v[192:195], v151 offset:3072
	ds_read_b128 v[196:199], v151 offset:4096
	ds_read_b128 v[200:203], v151 offset:5120
	ds_read_b128 v[204:207], v151 offset:6144
	ds_read_b128 v[208:211], v151 offset:7168
	global_load_lds_dwordx4 v[144:145], off
	v_lshl_add_u64 v[144:145], s[50:51], 0, v[138:139]
	s_add_i32 m0, s5, 0xe000
	s_nop 0
	global_load_lds_dwordx4 v[144:145], off
	s_waitcnt vmcnt(8)
	s_waitcnt lgkmcnt(0)
	s_barrier
	s_setprio 1
	s_waitcnt lgkmcnt(0)
	v_mfma_f32_16x16x32_bf16 v[126:129], v[140:143], v[180:183], v[126:129]
	v_mfma_f32_16x16x32_bf16 v[122:125], v[156:159], v[180:183], v[122:125]
	v_mfma_f32_16x16x32_bf16 v[110:113], v[140:143], v[188:191], v[110:113]
	v_mfma_f32_16x16x32_bf16 v[106:109], v[156:159], v[188:191], v[106:109]
	v_mfma_f32_16x16x32_bf16 v[94:97], v[140:143], v[196:199], v[94:97]
	v_mfma_f32_16x16x32_bf16 v[90:93], v[156:159], v[196:199], v[90:93]
	v_mfma_f32_16x16x32_bf16 v[78:81], v[140:143], v[204:207], v[78:81]
	v_mfma_f32_16x16x32_bf16 v[74:77], v[156:159], v[204:207], v[74:77]
	v_mfma_f32_16x16x32_bf16 v[126:129], v[152:155], v[184:187], v[126:129]
	v_mfma_f32_16x16x32_bf16 v[122:125], v[160:163], v[184:187], v[122:125]
	v_mfma_f32_16x16x32_bf16 v[110:113], v[152:155], v[192:195], v[110:113]
	v_mfma_f32_16x16x32_bf16 v[106:109], v[160:163], v[192:195], v[106:109]
	v_mfma_f32_16x16x32_bf16 v[94:97], v[152:155], v[200:203], v[94:97]
	v_mfma_f32_16x16x32_bf16 v[90:93], v[160:163], v[200:203], v[90:93]
	v_mfma_f32_16x16x32_bf16 v[78:81], v[152:155], v[208:211], v[78:81]
	v_mfma_f32_16x16x32_bf16 v[74:77], v[160:163], v[208:211], v[74:77]
	s_setprio 0
	s_setprio 1
	v_mfma_f32_16x16x32_bf16 v[118:121], v[164:167], v[180:183], v[118:121]
	v_mfma_f32_16x16x32_bf16 v[114:117], v[172:175], v[180:183], v[114:117]
	v_mfma_f32_16x16x32_bf16 v[102:105], v[164:167], v[188:191], v[102:105]
	v_mfma_f32_16x16x32_bf16 v[98:101], v[172:175], v[188:191], v[98:101]
	v_mfma_f32_16x16x32_bf16 v[86:89], v[164:167], v[196:199], v[86:89]
	v_mfma_f32_16x16x32_bf16 v[82:85], v[172:175], v[196:199], v[82:85]
	v_mfma_f32_16x16x32_bf16 v[70:73], v[164:167], v[204:207], v[70:73]
	v_mfma_f32_16x16x32_bf16 v[66:69], v[172:175], v[204:207], v[66:69]
	v_mfma_f32_16x16x32_bf16 v[118:121], v[168:171], v[184:187], v[118:121]
	v_mfma_f32_16x16x32_bf16 v[114:117], v[176:179], v[184:187], v[114:117]
	v_mfma_f32_16x16x32_bf16 v[102:105], v[168:171], v[192:195], v[102:105]
	v_mfma_f32_16x16x32_bf16 v[98:101], v[176:179], v[192:195], v[98:101]
	v_mfma_f32_16x16x32_bf16 v[86:89], v[168:171], v[200:203], v[86:89]
	v_mfma_f32_16x16x32_bf16 v[82:85], v[176:179], v[200:203], v[82:85]
	v_mfma_f32_16x16x32_bf16 v[70:73], v[168:171], v[208:211], v[70:73]
	v_mfma_f32_16x16x32_bf16 v[66:69], v[176:179], v[208:211], v[66:69]
	s_setprio 0
	s_barrier
	s_add_i32 s60, s60, s4
	v_lshl_add_u64 v[144:145], s[10:11], 0, v[0:1]
	s_mov_b32 m0, s60
	ds_read_b128 v[180:183], v151 offset:16384
	ds_read_b128 v[184:187], v151 offset:17408
	ds_read_b128 v[188:191], v151 offset:18432
	ds_read_b128 v[192:195], v151 offset:19456
	ds_read_b128 v[196:199], v151 offset:20480
	ds_read_b128 v[200:203], v151 offset:21504
	ds_read_b128 v[204:207], v151 offset:22528
	ds_read_b128 v[208:211], v151 offset:23552
	global_load_lds_dwordx4 v[144:145], off
	s_add_i32 m0, s60, 0x2000
	s_add_u32 s60, s10, 0x20000
	v_lshl_add_u64 v[212:213], s[10:11], 0, v[134:135]
	s_addc_u32 s61, s11, 0
	s_add_i32 s62, s62, s4
	global_load_lds_dwordx4 v[212:213], off
	v_lshl_add_u64 v[214:215], s[60:61], 0, v[0:1]
	s_mov_b32 m0, s62
	v_lshl_add_u64 v[216:217], s[52:53], 0, v[132:133]
	global_load_lds_dwordx4 v[214:215], off
	v_lshl_add_u64 v[214:215], s[60:61], 0, v[134:135]
	s_add_i32 m0, s62, 0x2000
	s_nop 0
	global_load_lds_dwordx4 v[214:215], off
	v_lshl_add_u64 v[214:215], s[52:53], 0, v[130:131]
	s_mov_b32 m0, s5
	s_nop 0
	global_load_lds_dwordx4 v[214:215], off
	s_mov_b32 m0, s6
	s_nop 0
	global_load_lds_dwordx4 v[216:217], off
	s_waitcnt vmcnt(8)
	s_waitcnt lgkmcnt(0)
	s_barrier
; #define PG8_STAGE(bufoff, gbase, voff) do { _Pragma("unroll") for (int _i = 0; _i < 2; ++_i) \
;         __builtin_amdgcn_global_load_lds((const unsigned*)((const char*)(gbase) + (voff)[_i]), (PG8_LAS unsigned*)(lds + (bufoff) + ldsw + _i * 8192), 16, 0, 0); } while (0)
; #define PG8_LDA(dst, b, h) do { _Pragma("unroll") for (int m = 0; m < 4; ++m) _Pragma("unroll") for (int k = 0; k < 2; ++k) dst[m][k] = *(const PG8_LAS bf16x8*)(lds + PG8_SA(b, h) + aoff + m * 2048 + k * 1024); } while (0)
; #define PG8_LDB(dst, b, h) do { _Pragma("unroll") for (int n = 0; n < 2; ++n) _Pragma("unroll") for (int k = 0; k < 2; ++k) dst[n][k] = *(const PG8_LAS bf16x8*)(lds + PG8_SB(b, h) + boff + n * 2048 + k * 1024); } while (0)
; #define PG8_MMA(ai, bj, At, Bt) do { __builtin_amdgcn_s_setprio(1); _Pragma("unroll") for (int m = 0; m < 4; ++m) _Pragma("unroll") for (int n = 0; n < 2; ++n) _Pragma("unroll") for (int k = 0; k < 2; ++k) \
;         acc[ai][bj][m][n] = __builtin_amdgcn_mfma_f32_16x16x32_bf16(Bt[n][k], At[m][k], acc[ai][bj][m][n], 0, 0, 0); __builtin_amdgcn_s_setprio(0); } while (0)
; #define PG8_WAIT_V(n) asm volatile("s_waitcnt vmcnt(" #n ")" ::: "memory")
; #define PG8_WAIT_L(n) asm volatile("s_waitcnt lgkmcnt(" #n ")" ::: "memory")
; #define PG8_BAR __builtin_amdgcn_s_barrier()
; #define PG8_SCHED __builtin_amdgcn_sched_barrier(0)
; template <class Epi, class Sched, bool ALIGN_EPI = false, bool SP2 = false>
; __device__ __forceinline__ void gemm_phase(PG8_LAS unsigned char* lds, const Gemm g, const Sched& S, const Epi& E) {
;     ...
;             PG8_WAIT_V(8); PG8_WAIT_L(0); PG8_BAR; PG8_MMA(1, 0, At, B0); PG8_MMA(1, 1, At, B1); PG8_BAR; PG8_SCHED;
;             PG8_LDB(B0, 1, 0); PG8_LDB(B1, 1, 1); PG8_SCHED; PG8_LDA(At, 1, 0); PG8_STAGE(PG8_SA(0, 1), a2 + hstep, voffA);
;             PG8_WAIT_V(8); PG8_WAIT_L(0); PG8_BAR; PG8_MMA(0, 0, At, B0); PG8_MMA(0, 1, At, B1); PG8_BAR; PG8_SCHED;
	s_setprio 1
	s_waitcnt lgkmcnt(0)
	v_mfma_f32_16x16x32_bf16 v[62:65], v[140:143], v[180:183], v[62:65]
	v_mfma_f32_16x16x32_bf16 v[58:61], v[156:159], v[180:183], v[58:61]
	v_mfma_f32_16x16x32_bf16 v[46:49], v[140:143], v[188:191], v[46:49]
	v_mfma_f32_16x16x32_bf16 v[42:45], v[156:159], v[188:191], v[42:45]
	v_mfma_f32_16x16x32_bf16 v[30:33], v[140:143], v[196:199], v[30:33]
	v_mfma_f32_16x16x32_bf16 v[26:29], v[156:159], v[196:199], v[26:29]
	v_mfma_f32_16x16x32_bf16 v[14:17], v[140:143], v[204:207], v[14:17]
	v_mfma_f32_16x16x32_bf16 v[10:13], v[156:159], v[204:207], v[10:13]
	v_mfma_f32_16x16x32_bf16 v[62:65], v[152:155], v[184:187], v[62:65]
	v_mfma_f32_16x16x32_bf16 v[58:61], v[160:163], v[184:187], v[58:61]
	v_mfma_f32_16x16x32_bf16 v[46:49], v[152:155], v[192:195], v[46:49]
	v_mfma_f32_16x16x32_bf16 v[42:45], v[160:163], v[192:195], v[42:45]
	v_mfma_f32_16x16x32_bf16 v[30:33], v[152:155], v[200:203], v[30:33]
	v_mfma_f32_16x16x32_bf16 v[26:29], v[160:163], v[200:203], v[26:29]
	v_mfma_f32_16x16x32_bf16 v[14:17], v[152:155], v[208:211], v[14:17]
	v_mfma_f32_16x16x32_bf16 v[10:13], v[160:163], v[208:211], v[10:13]
	s_setprio 0
	s_setprio 1
	v_mfma_f32_16x16x32_bf16 v[54:57], v[164:167], v[180:183], v[54:57]
	v_mfma_f32_16x16x32_bf16 v[50:53], v[172:175], v[180:183], v[50:53]
	v_mfma_f32_16x16x32_bf16 v[38:41], v[164:167], v[188:191], v[38:41]
	v_mfma_f32_16x16x32_bf16 v[34:37], v[172:175], v[188:191], v[34:37]
	v_mfma_f32_16x16x32_bf16 v[22:25], v[164:167], v[196:199], v[22:25]
	v_mfma_f32_16x16x32_bf16 v[18:21], v[172:175], v[196:199], v[18:21]
	v_mfma_f32_16x16x32_bf16 v[6:9], v[164:167], v[204:207], v[6:9]
	v_mfma_f32_16x16x32_bf16 v[2:5], v[172:175], v[204:207], v[2:5]
	v_mfma_f32_16x16x32_bf16 v[54:57], v[168:171], v[184:187], v[54:57]
	v_mfma_f32_16x16x32_bf16 v[50:53], v[176:179], v[184:187], v[50:53]
	v_mfma_f32_16x16x32_bf16 v[38:41], v[168:171], v[192:195], v[38:41]
	v_mfma_f32_16x16x32_bf16 v[34:37], v[176:179], v[192:195], v[34:37]
	v_mfma_f32_16x16x32_bf16 v[22:25], v[168:171], v[200:203], v[22:25]
	v_mfma_f32_16x16x32_bf16 v[18:21], v[176:179], v[200:203], v[18:21]
	v_mfma_f32_16x16x32_bf16 v[6:9], v[168:171], v[208:211], v[6:9]
	v_mfma_f32_16x16x32_bf16 v[2:5], v[176:179], v[208:211], v[2:5]
	s_setprio 0
	s_barrier
	s_add_i32 s60, 0, 0x18000
	v_add_u32_e32 v146, s60, v149
	s_add_i32 s61, 0, 0x1c000
	ds_read_b128 v[140:143], v146
	ds_read_b128 v[152:155], v146 offset:1024
	ds_read_b128 v[156:159], v146 offset:2048
	ds_read_b128 v[160:163], v146 offset:3072
	v_add_u32_e32 v146, s61, v149
	ds_read_b128 v[164:167], v146
	ds_read_b128 v[168:171], v146 offset:1024
	ds_read_b128 v[172:175], v146 offset:2048
	ds_read_b128 v[176:179], v146 offset:3072
	s_add_u32 s52, s52, 0x80000
	s_addc_u32 s53, s53, 0
	s_mov_b32 m0, s7
	v_lshl_add_u64 v[222:223], s[52:53], 0, v[130:131]
	ds_read_b128 v[180:183], v151 offset:32768
	ds_read_b128 v[184:187], v151 offset:33792
	ds_read_b128 v[188:191], v151 offset:34816
	ds_read_b128 v[192:195], v151 offset:35840
	ds_read_b128 v[196:199], v151 offset:36864
	ds_read_b128 v[200:203], v151 offset:37888
	ds_read_b128 v[204:207], v151 offset:38912
	ds_read_b128 v[208:211], v151 offset:39936
	global_load_lds_dwordx4 v[222:223], off
	v_lshl_add_u64 v[222:223], s[52:53], 0, v[132:133]
	s_mov_b32 m0, s17
	s_nop 0
	global_load_lds_dwordx4 v[222:223], off
	s_waitcnt vmcnt(8)
	s_waitcnt lgkmcnt(0)
	s_barrier
	s_setprio 1
	s_waitcnt lgkmcnt(0)
	v_mfma_f32_16x16x32_bf16 v[126:129], v[140:143], v[180:183], v[126:129]
	v_mfma_f32_16x16x32_bf16 v[122:125], v[156:159], v[180:183], v[122:125]
	v_mfma_f32_16x16x32_bf16 v[110:113], v[140:143], v[188:191], v[110:113]
	v_mfma_f32_16x16x32_bf16 v[106:109], v[156:159], v[188:191], v[106:109]
	v_mfma_f32_16x16x32_bf16 v[94:97], v[140:143], v[196:199], v[94:97]
	v_mfma_f32_16x16x32_bf16 v[90:93], v[156:159], v[196:199], v[90:93]
	v_mfma_f32_16x16x32_bf16 v[78:81], v[140:143], v[204:207], v[78:81]
	v_mfma_f32_16x16x32_bf16 v[74:77], v[156:159], v[204:207], v[74:77]
	v_mfma_f32_16x16x32_bf16 v[126:129], v[152:155], v[184:187], v[126:129]
	v_mfma_f32_16x16x32_bf16 v[122:125], v[160:163], v[184:187], v[122:125]
	v_mfma_f32_16x16x32_bf16 v[110:113], v[152:155], v[192:195], v[110:113]
	v_mfma_f32_16x16x32_bf16 v[106:109], v[160:163], v[192:195], v[106:109]
	v_mfma_f32_16x16x32_bf16 v[94:97], v[152:155], v[200:203], v[94:97]
	v_mfma_f32_16x16x32_bf16 v[90:93], v[160:163], v[200:203], v[90:93]
	v_mfma_f32_16x16x32_bf16 v[78:81], v[152:155], v[208:211], v[78:81]
	v_mfma_f32_16x16x32_bf16 v[74:77], v[160:163], v[208:211], v[74:77]
	s_setprio 0
	s_setprio 1
	v_mfma_f32_16x16x32_bf16 v[118:121], v[164:167], v[180:183], v[118:121]
	v_mfma_f32_16x16x32_bf16 v[114:117], v[172:175], v[180:183], v[114:117]
	v_mfma_f32_16x16x32_bf16 v[102:105], v[164:167], v[188:191], v[102:105]
	v_mfma_f32_16x16x32_bf16 v[98:101], v[172:175], v[188:191], v[98:101]
	v_mfma_f32_16x16x32_bf16 v[86:89], v[164:167], v[196:199], v[86:89]
	v_mfma_f32_16x16x32_bf16 v[82:85], v[172:175], v[196:199], v[82:85]
	v_mfma_f32_16x16x32_bf16 v[70:73], v[164:167], v[204:207], v[70:73]
	v_mfma_f32_16x16x32_bf16 v[66:69], v[172:175], v[204:207], v[66:69]
	v_mfma_f32_16x16x32_bf16 v[118:121], v[168:171], v[184:187], v[118:121]
	v_mfma_f32_16x16x32_bf16 v[114:117], v[176:179], v[184:187], v[114:117]
	v_mfma_f32_16x16x32_bf16 v[102:105], v[168:171], v[192:195], v[102:105]
	v_mfma_f32_16x16x32_bf16 v[98:101], v[176:179], v[192:195], v[98:101]
	v_mfma_f32_16x16x32_bf16 v[86:89], v[168:171], v[200:203], v[86:89]
	v_mfma_f32_16x16x32_bf16 v[82:85], v[176:179], v[200:203], v[82:85]
	v_mfma_f32_16x16x32_bf16 v[70:73], v[168:171], v[208:211], v[70:73]
	v_mfma_f32_16x16x32_bf16 v[66:69], v[176:179], v[208:211], v[66:69]
	s_setprio 0
	s_barrier
; #define PG8_STAGE(bufoff, gbase, voff) do { _Pragma("unroll") for (int _i = 0; _i < 2; ++_i) \
;         __builtin_amdgcn_global_load_lds((const unsigned*)((const char*)(gbase) + (voff)[_i]), (PG8_LAS unsigned*)(lds + (bufoff) + ldsw + _i * 8192), 16, 0, 0); } while (0)
; #define PG8_LDA(dst, b, h) do { _Pragma("unroll") for (int m = 0; m < 4; ++m) _Pragma("unroll") for (int k = 0; k < 2; ++k) dst[m][k] = *(const PG8_LAS bf16x8*)(lds + PG8_SA(b, h) + aoff + m * 2048 + k * 1024); } while (0)
; #define PG8_MMA(ai, bj, At, Bt) do { __builtin_amdgcn_s_setprio(1); _Pragma("unroll") for (int m = 0; m < 4; ++m) _Pragma("unroll") for (int n = 0; n < 2; ++n) _Pragma("unroll") for (int k = 0; k < 2; ++k) \
;         acc[ai][bj][m][n] = __builtin_amdgcn_mfma_f32_16x16x32_bf16(Bt[n][k], At[m][k], acc[ai][bj][m][n], 0, 0, 0); __builtin_amdgcn_s_setprio(0); } while (0)
; #define PG8_WAIT_V(n) asm volatile("s_waitcnt vmcnt(" #n ")" ::: "memory")
; #define PG8_WAIT_L(n) asm volatile("s_waitcnt lgkmcnt(" #n ")" ::: "memory")
; #define PG8_BAR __builtin_amdgcn_s_barrier()
; #define PG8_SCHED __builtin_amdgcn_sched_barrier(0)
;     __device__ __forceinline__ void operator()(const f32x4 (&acc)[2][2][4][2], const Unit& u, int wr, int wc, int fr, int fq) const {
;         const int row0 = u.pm * BM + wr * 64 + fr; const bool second = split > 0 && u.pn >= split; const int col0 = (second ? u.pn - split : u.pn) * BM + wc * 32 + 8 * fq;
;         bf16_t* const Ob = second ? O2 : O; const int ld = second ? ldc2 : ldc;
; #pragma unroll
;         for (int ai = 0; ai < 2; ++ai)
; #pragma unroll
;             for (int m = 0; m < 4; ++m) { bf16_t* rowp = Ob + (size_t)(row0 + ai * HALF + m * 16) * ld + col0;
;                 float rs = 1.f; if (ss) rs = __builtin_amdgcn_rsqf((float)ss[row0 + ai * HALF + m * 16] * (1.f / (2048.f * 262144.f)) + 1e-6f);
; template <class Epi, class Sched, bool ALIGN_EPI = false, bool SP2 = false>
; __device__ __forceinline__ void gemm_phase(PG8_LAS unsigned char* lds, const Gemm g, const Sched& S, const Epi& E) {
;     ...
;             PG8_LDA(At, 1, 1); PG8_STAGE(PG8_SB(1, 0), b3, voffB); PG8_STAGE(PG8_SB(1, 1), b3 + hstep, voffB); PG8_STAGE(PG8_SA(1, 0), a3, voffA);
;             PG8_WAIT_V(8); PG8_WAIT_L(0); PG8_BAR; PG8_MMA(1, 0, At, B0); PG8_MMA(1, 1, At, B1); PG8_BAR; PG8_SCHED;
	s_add_i32 s52, s60, s4
	v_lshl_add_u64 v[144:145], v[144:145], 0, s[34:35]
	s_mov_b32 m0, s52
	ds_read_b128 v[180:183], v151 offset:49152
	ds_read_b128 v[184:187], v151 offset:50176
	ds_read_b128 v[188:191], v151 offset:51200
	ds_read_b128 v[192:195], v151 offset:52224
	ds_read_b128 v[196:199], v151 offset:53248
	ds_read_b128 v[200:203], v151 offset:54272
	ds_read_b128 v[204:207], v151 offset:55296
	ds_read_b128 v[208:211], v151 offset:56320
	global_load_lds_dwordx4 v[144:145], off
	s_add_i32 m0, s52, 0x2000
	s_add_u32 s10, s10, 0x20080
	v_lshl_add_u64 v[144:145], v[212:213], 0, s[34:35]
	s_addc_u32 s11, s11, 0
	s_add_i32 s52, s61, s4
	global_load_lds_dwordx4 v[144:145], off
	v_lshl_add_u64 v[144:145], s[10:11], 0, v[0:1]
	s_mov_b32 m0, s52
	s_nop 0
	global_load_lds_dwordx4 v[144:145], off
	v_lshl_add_u64 v[144:145], s[10:11], 0, v[134:135]
	s_add_i32 m0, s52, 0x2000
	s_nop 0
	global_load_lds_dwordx4 v[144:145], off
	v_lshl_add_u64 v[144:145], v[214:215], 0, s[34:35]
	s_mov_b32 m0, s30
	s_nop 0
	global_load_lds_dwordx4 v[144:145], off
	v_lshl_add_u64 v[144:145], v[216:217], 0, s[34:35]
	s_mov_b32 m0, s47
	s_nop 0
	global_load_lds_dwordx4 v[144:145], off
	s_waitcnt vmcnt(8)
	s_waitcnt lgkmcnt(0)
	s_barrier
	s_setprio 1
	s_waitcnt lgkmcnt(0)
	v_mfma_f32_16x16x32_bf16 v[62:65], v[140:143], v[180:183], v[62:65]
	v_mfma_f32_16x16x32_bf16 v[58:61], v[156:159], v[180:183], v[58:61]
	v_mfma_f32_16x16x32_bf16 v[46:49], v[140:143], v[188:191], v[46:49]
	v_mfma_f32_16x16x32_bf16 v[42:45], v[156:159], v[188:191], v[42:45]
	v_mfma_f32_16x16x32_bf16 v[30:33], v[140:143], v[196:199], v[30:33]
	v_mfma_f32_16x16x32_bf16 v[26:29], v[156:159], v[196:199], v[26:29]
	v_mfma_f32_16x16x32_bf16 v[14:17], v[140:143], v[204:207], v[14:17]
	v_mfma_f32_16x16x32_bf16 v[10:13], v[156:159], v[204:207], v[10:13]
	v_mfma_f32_16x16x32_bf16 v[62:65], v[152:155], v[184:187], v[62:65]
	v_mfma_f32_16x16x32_bf16 v[58:61], v[160:163], v[184:187], v[58:61]
	v_mfma_f32_16x16x32_bf16 v[46:49], v[152:155], v[192:195], v[46:49]
	v_mfma_f32_16x16x32_bf16 v[42:45], v[160:163], v[192:195], v[42:45]
	v_mfma_f32_16x16x32_bf16 v[30:33], v[152:155], v[200:203], v[30:33]
	v_mfma_f32_16x16x32_bf16 v[26:29], v[160:163], v[200:203], v[26:29]
	v_mfma_f32_16x16x32_bf16 v[14:17], v[152:155], v[208:211], v[14:17]
	v_mfma_f32_16x16x32_bf16 v[10:13], v[160:163], v[208:211], v[10:13]
	s_setprio 0
	s_setprio 1
	v_mfma_f32_16x16x32_bf16 v[54:57], v[164:167], v[180:183], v[54:57]
	v_mfma_f32_16x16x32_bf16 v[50:53], v[172:175], v[180:183], v[50:53]
	v_mfma_f32_16x16x32_bf16 v[38:41], v[164:167], v[188:191], v[38:41]
	v_mfma_f32_16x16x32_bf16 v[34:37], v[172:175], v[188:191], v[34:37]
	v_mfma_f32_16x16x32_bf16 v[22:25], v[164:167], v[196:199], v[22:25]
	v_mfma_f32_16x16x32_bf16 v[18:21], v[172:175], v[196:199], v[18:21]
	v_mfma_f32_16x16x32_bf16 v[6:9], v[164:167], v[204:207], v[6:9]
	v_mfma_f32_16x16x32_bf16 v[2:5], v[172:175], v[204:207], v[2:5]
	v_mfma_f32_16x16x32_bf16 v[54:57], v[168:171], v[184:187], v[54:57]
	v_mfma_f32_16x16x32_bf16 v[50:53], v[176:179], v[184:187], v[50:53]
	v_mfma_f32_16x16x32_bf16 v[38:41], v[168:171], v[192:195], v[38:41]
	v_mfma_f32_16x16x32_bf16 v[34:37], v[176:179], v[192:195], v[34:37]
	v_mfma_f32_16x16x32_bf16 v[22:25], v[168:171], v[200:203], v[22:25]
	v_mfma_f32_16x16x32_bf16 v[18:21], v[176:179], v[200:203], v[18:21]
	v_mfma_f32_16x16x32_bf16 v[6:9], v[168:171], v[208:211], v[6:9]
	v_mfma_f32_16x16x32_bf16 v[2:5], v[176:179], v[208:211], v[2:5]
	s_setprio 0
	s_barrier
	s_add_i32 s59, s59, 2
	s_add_u32 s50, s50, 0x100
	s_addc_u32 s51, s51, 0
	s_add_u32 s57, s57, 0x100
	s_addc_u32 s58, s58, 0
	s_cmp_gt_u32 s59, 29
	s_cbranch_scc0 .LBB0_559
	s_and_b64 vcc, exec, s[14:15]
	s_cbranch_vccz .LBB0_562
	s_barrier
.LBB0_562:
	v_lshl_add_u32 v140, s42, 8, v147
	v_ashrrev_i32_e32 v141, 31, v140
	v_lshl_add_u64 v[142:143], v[140:141], 3, s[12:13]
	s_and_b64 vcc, exec, s[20:21]
	s_cbranch_vccz .Lpfl_a
	global_load_dwordx2 v[160:161], v[142:143], off
	global_load_dwordx2 v[162:163], v[142:143], off offset:128
	global_load_dwordx2 v[164:165], v[142:143], off offset:256
	global_load_dwordx2 v[166:167], v[142:143], off offset:384
	global_load_dwordx2 v[168:169], v[142:143], off offset:1024
	global_load_dwordx2 v[170:171], v[142:143], off offset:1152
	global_load_dwordx2 v[172:173], v[142:143], off offset:1280
	global_load_dwordx2 v[174:175], v[142:143], off offset:1408
; __device__ __forceinline__ unsigned cvt_pk_bf16(float lo, float hi) { unsigned r; asm volatile("v_cvt_pk_bf16_f32 %0, %1, %2" : "=v"(r) : "v"(lo), "v"(hi)); return r; }
;     __device__ __forceinline__ void operator()(const f32x4 (&acc)[2][2][4][2], const Unit& u, int wr, int wc, int fr, int fq) const {
;         const int row0 = u.pm * BM + wr * 64 + fr; const bool second = split > 0 && u.pn >= split; const int col0 = (second ? u.pn - split : u.pn) * BM + wc * 32 + 8 * fq;
;         bf16_t* const Ob = second ? O2 : O; const int ld = second ? ldc2 : ldc;
; #pragma unroll
;         for (int ai = 0; ai < 2; ++ai)
; #pragma unroll
;             for (int m = 0; m < 4; ++m) { bf16_t* rowp = Ob + (size_t)(row0 + ai * HALF + m * 16) * ld + col0;
;                 float rs = 1.f; if (ss) rs = __builtin_amdgcn_rsqf((float)ss[row0 + ai * HALF + m * 16] * (1.f / (2048.f * 262144.f)) + 1e-6f);
; #pragma unroll
;                 for (int bj = 0; bj < 2; ++bj) { const f32x4 v0 = acc[ai][bj][m][0] * rs, v1 = acc[ai][bj][m][1] * rs;
;                     u32x4 w; w.x = cvt_pk_bf16(v0[0], v0[1]); w.y = cvt_pk_bf16(v0[2], v0[3]); w.z = cvt_pk_bf16(v1[0], v1[1]); w.w = cvt_pk_bf16(v1[2], v1[3]);
;                     *(u32x4*)(rowp + bj * HALF) = w; } }
.Lpfl_a:
	s_cmp_gt_i32 s16, 8
	s_cselect_b32 s11, -9, 0
	s_cselect_b32 s23, s81, s2
	s_cselect_b32 s37, s80, s1
	s_movk_i32 s10, 0x900
	s_cselect_b32 s10, 0x1080, s10
	s_add_i32 s11, s11, s16
	v_and_b32_e32 v144, 0x60, v150
	v_add_u32_e32 v144, v144, v150
	v_lshl_or_b32 v144, s11, 8, v144
	v_and_b32_e32 v146, 8, v227
	v_sub_u32_e32 v148, v140, v146
	v_lshl_add_u32 v144, v146, 2, v144
	v_mov_b32_e32 v145, 0
	v_mov_b32_e32 v154, s37
	v_mov_b32_e32 v155, s23
	v_mad_i64_i32 v[152:153], s[50:51], s10, v148, 0
	v_lshl_add_u64 v[144:145], v[144:145], 1, v[154:155]
	v_lshl_add_u64 v[152:153], v[152:153], 1, v[144:145]
	s_lshl_b32 s23, s10, 4
	s_add_i32 s23, s23, 64
	v_lshlrev_b32_e32 v146, 4, v146
	v_sub_u32_e32 v154, s23, v146
	v_mov_b32_e32 v155, 0
	s_lshl_b32 s50, s10, 5
	s_mov_b32 s51, 0
	s_mul_i32 s42, s10, 0xa0
	s_mov_b32 s43, 0
	s_and_b64 vcc, exec, s[20:21]
	s_cbranch_vccz .Lpfl_b
	s_waitcnt vmcnt(0)
	v_ffbh_u32_e32 v141, v161
	v_min_u32_e32 v141, 32, v141
	v_lshlrev_b64 v[160:161], v141, v[160:161]
	v_min_u32_e32 v160, 1, v160
	v_or_b32_e32 v160, v161, v160
	v_cvt_f32_u32_e32 v160, v160
	v_sub_u32_e32 v141, 32, v141
	v_ldexp_f32 v160, v160, v141
	v_fmamk_f32 v160, v160, 0x31000000, v232
	v_rsq_f32_e32 v160, v160
	v_ffbh_u32_e32 v141, v163
	v_min_u32_e32 v141, 32, v141
	v_lshlrev_b64 v[162:163], v141, v[162:163]
	v_min_u32_e32 v162, 1, v162
	v_or_b32_e32 v162, v163, v162
	v_cvt_f32_u32_e32 v162, v162
	v_sub_u32_e32 v141, 32, v141
	v_ldexp_f32 v162, v162, v141
	v_fmamk_f32 v162, v162, 0x31000000, v232
	v_rsq_f32_e32 v162, v162
	v_ffbh_u32_e32 v141, v165
	v_min_u32_e32 v141, 32, v141
	v_lshlrev_b64 v[164:165], v141, v[164:165]
	v_min_u32_e32 v164, 1, v164
	v_or_b32_e32 v164, v165, v164
	v_cvt_f32_u32_e32 v164, v164
	v_sub_u32_e32 v141, 32, v141
	v_ldexp_f32 v164, v164, v141
	v_fmamk_f32 v164, v164, 0x31000000, v232
	v_rsq_f32_e32 v164, v164
	v_ffbh_u32_e32 v141, v167
	v_min_u32_e32 v141, 32, v141
	v_lshlrev_b64 v[166:167], v141, v[166:167]
	v_min_u32_e32 v166, 1, v166
	v_or_b32_e32 v166, v167, v166
	v_cvt_f32_u32_e32 v166, v166
	v_sub_u32_e32 v141, 32, v141
	v_ldexp_f32 v166, v166, v141
	v_fmamk_f32 v166, v166, 0x31000000, v232
	v_rsq_f32_e32 v166, v166
	v_ffbh_u32_e32 v141, v169
	v_min_u32_e32 v141, 32, v141
	v_lshlrev_b64 v[168:169], v141, v[168:169]
	v_min_u32_e32 v168, 1, v168
	v_or_b32_e32 v168, v169, v168
	v_cvt_f32_u32_e32 v168, v168
	v_sub_u32_e32 v141, 32, v141
	v_ldexp_f32 v168, v168, v141
	v_fmamk_f32 v168, v168, 0x31000000, v232
	v_rsq_f32_e32 v168, v168
	v_ffbh_u32_e32 v141, v171
	v_min_u32_e32 v141, 32, v141
	v_lshlrev_b64 v[170:171], v141, v[170:171]
	v_min_u32_e32 v170, 1, v170
	v_or_b32_e32 v170, v171, v170
	v_cvt_f32_u32_e32 v170, v170
	v_sub_u32_e32 v141, 32, v141
	v_ldexp_f32 v170, v170, v141
	v_fmamk_f32 v170, v170, 0x31000000, v232
	v_rsq_f32_e32 v170, v170
	v_ffbh_u32_e32 v141, v173
	v_min_u32_e32 v141, 32, v141
	v_lshlrev_b64 v[172:173], v141, v[172:173]
	v_min_u32_e32 v172, 1, v172
	v_or_b32_e32 v172, v173, v172
	v_cvt_f32_u32_e32 v172, v172
	v_sub_u32_e32 v141, 32, v141
	v_ldexp_f32 v172, v172, v141
	v_fmamk_f32 v172, v172, 0x31000000, v232
	v_rsq_f32_e32 v172, v172
	v_ffbh_u32_e32 v141, v175
	v_min_u32_e32 v141, 32, v141
	v_lshlrev_b64 v[174:175], v141, v[174:175]
	v_min_u32_e32 v174, 1, v174
	v_or_b32_e32 v174, v175, v174
	v_cvt_f32_u32_e32 v174, v174
	v_sub_u32_e32 v141, 32, v141
	v_ldexp_f32 v174, v174, v141
	v_fmamk_f32 v174, v174, 0x31000000, v232
	v_rsq_f32_e32 v174, v174
	s_branch .Lpfl_c
.Lpfl_b:
	v_mov_b32_e32 v160, 1.0
	v_mov_b32_e32 v162, 1.0
	v_mov_b32_e32 v164, 1.0
	v_mov_b32_e32 v166, 1.0
	v_mov_b32_e32 v168, 1.0
	v_mov_b32_e32 v170, 1.0
	v_mov_b32_e32 v172, 1.0
	v_mov_b32_e32 v174, 1.0
.Lpfl_c:
	s_nop 0
	v_pk_mul_f32 v[114:115], v[114:115], v[160:161] op_sel_hi:[1,0]
	v_pk_mul_f32 v[116:117], v[116:117], v[160:161] op_sel_hi:[1,0]
	v_pk_mul_f32 v[118:119], v[118:119], v[160:161] op_sel_hi:[1,0]
	v_pk_mul_f32 v[120:121], v[120:121], v[160:161] op_sel_hi:[1,0]
	v_pk_mul_f32 v[122:123], v[122:123], v[160:161] op_sel_hi:[1,0]
	v_pk_mul_f32 v[124:125], v[124:125], v[160:161] op_sel_hi:[1,0]
	v_pk_mul_f32 v[126:127], v[126:127], v[160:161] op_sel_hi:[1,0]
	v_pk_mul_f32 v[128:129], v[128:129], v[160:161] op_sel_hi:[1,0]
	v_cvt_pk_bf16_f32 v118, v118, v119
	v_cvt_pk_bf16_f32 v119, v120, v121
	v_cvt_pk_bf16_f32 v120, v114, v115
	v_cvt_pk_bf16_f32 v121, v116, v117
	v_cvt_pk_bf16_f32 v126, v126, v127
	v_cvt_pk_bf16_f32 v127, v128, v129
	v_cvt_pk_bf16_f32 v128, v122, v123
	v_cvt_pk_bf16_f32 v129, v124, v125
	v_mov_b32_e32 v122, v126
	v_mov_b32_e32 v123, v127
	v_mov_b32_e32 v124, v128
	v_mov_b32_e32 v125, v129
	v_mov_b32_dpp v122, v118 row_ror:8 row_mask:0xf bank_mask:0xc
	v_mov_b32_dpp v123, v119 row_ror:8 row_mask:0xf bank_mask:0xc
	v_mov_b32_dpp v124, v120 row_ror:8 row_mask:0xf bank_mask:0xc
	v_mov_b32_dpp v125, v121 row_ror:8 row_mask:0xf bank_mask:0xc
	v_mov_b32_dpp v126, v118 row_ror:8 row_mask:0xf bank_mask:0x3
	v_mov_b32_dpp v127, v119 row_ror:8 row_mask:0xf bank_mask:0x3
	v_mov_b32_dpp v128, v120 row_ror:8 row_mask:0xf bank_mask:0x3
	v_mov_b32_dpp v129, v121 row_ror:8 row_mask:0xf bank_mask:0x3
	v_lshl_add_u64 v[142:143], v[152:153], 0, v[154:155]
	global_store_dwordx4 v[152:153], v[122:125], off
	global_store_dwordx4 v[142:143], v[126:129], off
	v_lshl_add_u64 v[152:153], v[152:153], 0, s[50:51]
	v_pk_mul_f32 v[98:99], v[98:99], v[162:163] op_sel_hi:[1,0]
	v_pk_mul_f32 v[100:101], v[100:101], v[162:163] op_sel_hi:[1,0]
	v_pk_mul_f32 v[102:103], v[102:103], v[162:163] op_sel_hi:[1,0]
	v_pk_mul_f32 v[104:105], v[104:105], v[162:163] op_sel_hi:[1,0]
	v_pk_mul_f32 v[106:107], v[106:107], v[162:163] op_sel_hi:[1,0]
; __device__ __forceinline__ unsigned cvt_pk_bf16(float lo, float hi) { unsigned r; asm volatile("v_cvt_pk_bf16_f32 %0, %1, %2" : "=v"(r) : "v"(lo), "v"(hi)); return r; }
;     __device__ __forceinline__ void operator()(const f32x4 (&acc)[2][2][4][2], const Unit& u, int wr, int wc, int fr, int fq) const {
;     ...
;             for (int m = 0; m < 4; ++m) { bf16_t* rowp = Ob + (size_t)(row0 + ai * HALF + m * 16) * ld + col0;
;                 float rs = 1.f; if (ss) rs = __builtin_amdgcn_rsqf((float)ss[row0 + ai * HALF + m * 16] * (1.f / (2048.f * 262144.f)) + 1e-6f);
; #pragma unroll
;                 for (int bj = 0; bj < 2; ++bj) { const f32x4 v0 = acc[ai][bj][m][0] * rs, v1 = acc[ai][bj][m][1] * rs;
;                     u32x4 w; w.x = cvt_pk_bf16(v0[0], v0[1]); w.y = cvt_pk_bf16(v0[2], v0[3]); w.z = cvt_pk_bf16(v1[0], v1[1]); w.w = cvt_pk_bf16(v1[2], v1[3]);
;                     *(u32x4*)(rowp + bj * HALF) = w; } }
	v_pk_mul_f32 v[108:109], v[108:109], v[162:163] op_sel_hi:[1,0]
	v_pk_mul_f32 v[110:111], v[110:111], v[162:163] op_sel_hi:[1,0]
	v_pk_mul_f32 v[112:113], v[112:113], v[162:163] op_sel_hi:[1,0]
	v_cvt_pk_bf16_f32 v102, v102, v103
	v_cvt_pk_bf16_f32 v103, v104, v105
	v_cvt_pk_bf16_f32 v104, v98, v99
	v_cvt_pk_bf16_f32 v105, v100, v101
	v_cvt_pk_bf16_f32 v110, v110, v111
	v_cvt_pk_bf16_f32 v111, v112, v113
	v_cvt_pk_bf16_f32 v112, v106, v107
	v_cvt_pk_bf16_f32 v113, v108, v109
	v_mov_b32_e32 v106, v110
	v_mov_b32_e32 v107, v111
	v_mov_b32_e32 v108, v112
	v_mov_b32_e32 v109, v113
	v_mov_b32_dpp v106, v102 row_ror:8 row_mask:0xf bank_mask:0xc
	v_mov_b32_dpp v107, v103 row_ror:8 row_mask:0xf bank_mask:0xc
	v_mov_b32_dpp v108, v104 row_ror:8 row_mask:0xf bank_mask:0xc
	v_mov_b32_dpp v109, v105 row_ror:8 row_mask:0xf bank_mask:0xc
	v_mov_b32_dpp v110, v102 row_ror:8 row_mask:0xf bank_mask:0x3
	v_mov_b32_dpp v111, v103 row_ror:8 row_mask:0xf bank_mask:0x3
	v_mov_b32_dpp v112, v104 row_ror:8 row_mask:0xf bank_mask:0x3
	v_mov_b32_dpp v113, v105 row_ror:8 row_mask:0xf bank_mask:0x3
	v_lshl_add_u64 v[142:143], v[152:153], 0, v[154:155]
	global_store_dwordx4 v[152:153], v[106:109], off
	global_store_dwordx4 v[142:143], v[110:113], off
	v_lshl_add_u64 v[152:153], v[152:153], 0, s[50:51]
	v_pk_mul_f32 v[82:83], v[82:83], v[164:165] op_sel_hi:[1,0]
	v_pk_mul_f32 v[84:85], v[84:85], v[164:165] op_sel_hi:[1,0]
	v_pk_mul_f32 v[86:87], v[86:87], v[164:165] op_sel_hi:[1,0]
	v_pk_mul_f32 v[88:89], v[88:89], v[164:165] op_sel_hi:[1,0]
	v_pk_mul_f32 v[90:91], v[90:91], v[164:165] op_sel_hi:[1,0]
	v_pk_mul_f32 v[92:93], v[92:93], v[164:165] op_sel_hi:[1,0]
	v_pk_mul_f32 v[94:95], v[94:95], v[164:165] op_sel_hi:[1,0]
	v_pk_mul_f32 v[96:97], v[96:97], v[164:165] op_sel_hi:[1,0]
	v_cvt_pk_bf16_f32 v86, v86, v87
	v_cvt_pk_bf16_f32 v87, v88, v89
	v_cvt_pk_bf16_f32 v88, v82, v83
	v_cvt_pk_bf16_f32 v89, v84, v85
	v_cvt_pk_bf16_f32 v94, v94, v95
	v_cvt_pk_bf16_f32 v95, v96, v97
	v_cvt_pk_bf16_f32 v96, v90, v91
	v_cvt_pk_bf16_f32 v97, v92, v93
	v_mov_b32_e32 v90, v94
	v_mov_b32_e32 v91, v95
	v_mov_b32_e32 v92, v96
	v_mov_b32_e32 v93, v97
	v_mov_b32_dpp v90, v86 row_ror:8 row_mask:0xf bank_mask:0xc
	v_mov_b32_dpp v91, v87 row_ror:8 row_mask:0xf bank_mask:0xc
	v_mov_b32_dpp v92, v88 row_ror:8 row_mask:0xf bank_mask:0xc
	v_mov_b32_dpp v93, v89 row_ror:8 row_mask:0xf bank_mask:0xc
	v_mov_b32_dpp v94, v86 row_ror:8 row_mask:0xf bank_mask:0x3
	v_mov_b32_dpp v95, v87 row_ror:8 row_mask:0xf bank_mask:0x3
	v_mov_b32_dpp v96, v88 row_ror:8 row_mask:0xf bank_mask:0x3
	v_mov_b32_dpp v97, v89 row_ror:8 row_mask:0xf bank_mask:0x3
	v_lshl_add_u64 v[142:143], v[152:153], 0, v[154:155]
	global_store_dwordx4 v[152:153], v[90:93], off
	global_store_dwordx4 v[142:143], v[94:97], off
	v_lshl_add_u64 v[152:153], v[152:153], 0, s[50:51]
	v_pk_mul_f32 v[66:67], v[66:67], v[166:167] op_sel_hi:[1,0]
	v_pk_mul_f32 v[68:69], v[68:69], v[166:167] op_sel_hi:[1,0]
	v_pk_mul_f32 v[70:71], v[70:71], v[166:167] op_sel_hi:[1,0]
	v_pk_mul_f32 v[72:73], v[72:73], v[166:167] op_sel_hi:[1,0]
	v_pk_mul_f32 v[74:75], v[74:75], v[166:167] op_sel_hi:[1,0]
	v_pk_mul_f32 v[76:77], v[76:77], v[166:167] op_sel_hi:[1,0]
	v_pk_mul_f32 v[78:79], v[78:79], v[166:167] op_sel_hi:[1,0]
	v_pk_mul_f32 v[80:81], v[80:81], v[166:167] op_sel_hi:[1,0]
	v_cvt_pk_bf16_f32 v70, v70, v71
	v_cvt_pk_bf16_f32 v71, v72, v73
	v_cvt_pk_bf16_f32 v72, v66, v67
	v_cvt_pk_bf16_f32 v73, v68, v69
	v_cvt_pk_bf16_f32 v78, v78, v79
	v_cvt_pk_bf16_f32 v79, v80, v81
	v_cvt_pk_bf16_f32 v80, v74, v75
	v_cvt_pk_bf16_f32 v81, v76, v77
	v_mov_b32_e32 v74, v78
	v_mov_b32_e32 v75, v79
	v_mov_b32_e32 v76, v80
	v_mov_b32_e32 v77, v81
	v_mov_b32_dpp v74, v70 row_ror:8 row_mask:0xf bank_mask:0xc
	v_mov_b32_dpp v75, v71 row_ror:8 row_mask:0xf bank_mask:0xc
	v_mov_b32_dpp v76, v72 row_ror:8 row_mask:0xf bank_mask:0xc
	v_mov_b32_dpp v77, v73 row_ror:8 row_mask:0xf bank_mask:0xc
	v_mov_b32_dpp v78, v70 row_ror:8 row_mask:0xf bank_mask:0x3
	v_mov_b32_dpp v79, v71 row_ror:8 row_mask:0xf bank_mask:0x3
	v_mov_b32_dpp v80, v72 row_ror:8 row_mask:0xf bank_mask:0x3
	v_mov_b32_dpp v81, v73 row_ror:8 row_mask:0xf bank_mask:0x3
	v_lshl_add_u64 v[142:143], v[152:153], 0, v[154:155]
	global_store_dwordx4 v[152:153], v[74:77], off
	global_store_dwordx4 v[142:143], v[78:81], off
	v_lshl_add_u64 v[152:153], v[152:153], 0, s[42:43]
	v_pk_mul_f32 v[50:51], v[50:51], v[168:169] op_sel_hi:[1,0]
	v_pk_mul_f32 v[52:53], v[52:53], v[168:169] op_sel_hi:[1,0]
	v_pk_mul_f32 v[54:55], v[54:55], v[168:169] op_sel_hi:[1,0]
	v_pk_mul_f32 v[56:57], v[56:57], v[168:169] op_sel_hi:[1,0]
	v_pk_mul_f32 v[58:59], v[58:59], v[168:169] op_sel_hi:[1,0]
	v_pk_mul_f32 v[60:61], v[60:61], v[168:169] op_sel_hi:[1,0]
	v_pk_mul_f32 v[62:63], v[62:63], v[168:169] op_sel_hi:[1,0]
	v_pk_mul_f32 v[64:65], v[64:65], v[168:169] op_sel_hi:[1,0]
	v_cvt_pk_bf16_f32 v54, v54, v55
	v_cvt_pk_bf16_f32 v55, v56, v57
	v_cvt_pk_bf16_f32 v56, v50, v51
	v_cvt_pk_bf16_f32 v57, v52, v53
	v_cvt_pk_bf16_f32 v62, v62, v63
	v_cvt_pk_bf16_f32 v63, v64, v65
	v_cvt_pk_bf16_f32 v64, v58, v59
	v_cvt_pk_bf16_f32 v65, v60, v61
	v_mov_b32_e32 v58, v62
	v_mov_b32_e32 v59, v63
	v_mov_b32_e32 v60, v64
	v_mov_b32_e32 v61, v65
	v_mov_b32_dpp v58, v54 row_ror:8 row_mask:0xf bank_mask:0xc
; __device__ __forceinline__ unsigned cvt_pk_bf16(float lo, float hi) { unsigned r; asm volatile("v_cvt_pk_bf16_f32 %0, %1, %2" : "=v"(r) : "v"(lo), "v"(hi)); return r; }
; #define PG8_BAR __builtin_amdgcn_s_barrier()
;     __device__ __forceinline__ void operator()(const f32x4 (&acc)[2][2][4][2], const Unit& u, int wr, int wc, int fr, int fq) const {
;     ...
;             for (int m = 0; m < 4; ++m) { bf16_t* rowp = Ob + (size_t)(row0 + ai * HALF + m * 16) * ld + col0;
;                 float rs = 1.f; if (ss) rs = __builtin_amdgcn_rsqf((float)ss[row0 + ai * HALF + m * 16] * (1.f / (2048.f * 262144.f)) + 1e-6f);
; #pragma unroll
;                 for (int bj = 0; bj < 2; ++bj) { const f32x4 v0 = acc[ai][bj][m][0] * rs, v1 = acc[ai][bj][m][1] * rs;
;                     u32x4 w; w.x = cvt_pk_bf16(v0[0], v0[1]); w.y = cvt_pk_bf16(v0[2], v0[3]); w.z = cvt_pk_bf16(v1[0], v1[1]); w.w = cvt_pk_bf16(v1[2], v1[3]);
;                     *(u32x4*)(rowp + bj * HALF) = w; } }
; template <class Epi, class Sched, bool ALIGN_EPI = false, bool SP2 = false>
; __device__ __forceinline__ void gemm_phase(PG8_LAS unsigned char* lds, const Gemm g, const Sched& S, const Epi& E) {
;     ...
;         if (!has_next) break;
; #pragma unroll
;         for (int a = 0; a < 2; ++a)
; #pragma unroll
;             for (int b = 0; b < 2; ++b)
; #pragma unroll
;                 for (int m = 0; m < 4; ++m)
; #pragma unroll
;                     for (int n = 0; n < 2; ++n) acc[a][b][m][n] = (f32x4){0.f, 0.f, 0.f, 0.f};
;         cur = nxt; cA = nA; cB = nB; ++ui;
;         if constexpr (ALIGN_EPI) { if (wr == 1) PG8_BAR; }
	v_mov_b32_dpp v59, v55 row_ror:8 row_mask:0xf bank_mask:0xc
	v_mov_b32_dpp v60, v56 row_ror:8 row_mask:0xf bank_mask:0xc
	v_mov_b32_dpp v61, v57 row_ror:8 row_mask:0xf bank_mask:0xc
	v_mov_b32_dpp v62, v54 row_ror:8 row_mask:0xf bank_mask:0x3
	v_mov_b32_dpp v63, v55 row_ror:8 row_mask:0xf bank_mask:0x3
	v_mov_b32_dpp v64, v56 row_ror:8 row_mask:0xf bank_mask:0x3
	v_mov_b32_dpp v65, v57 row_ror:8 row_mask:0xf bank_mask:0x3
	v_lshl_add_u64 v[142:143], v[152:153], 0, v[154:155]
	global_store_dwordx4 v[152:153], v[58:61], off
	global_store_dwordx4 v[142:143], v[62:65], off
	v_lshl_add_u64 v[152:153], v[152:153], 0, s[50:51]
	v_pk_mul_f32 v[34:35], v[34:35], v[170:171] op_sel_hi:[1,0]
	v_pk_mul_f32 v[36:37], v[36:37], v[170:171] op_sel_hi:[1,0]
	v_pk_mul_f32 v[38:39], v[38:39], v[170:171] op_sel_hi:[1,0]
	v_pk_mul_f32 v[40:41], v[40:41], v[170:171] op_sel_hi:[1,0]
	v_pk_mul_f32 v[42:43], v[42:43], v[170:171] op_sel_hi:[1,0]
	v_pk_mul_f32 v[44:45], v[44:45], v[170:171] op_sel_hi:[1,0]
	v_pk_mul_f32 v[46:47], v[46:47], v[170:171] op_sel_hi:[1,0]
	v_pk_mul_f32 v[48:49], v[48:49], v[170:171] op_sel_hi:[1,0]
	v_cvt_pk_bf16_f32 v38, v38, v39
	v_cvt_pk_bf16_f32 v39, v40, v41
	v_cvt_pk_bf16_f32 v40, v34, v35
	v_cvt_pk_bf16_f32 v41, v36, v37
	v_cvt_pk_bf16_f32 v46, v46, v47
	v_cvt_pk_bf16_f32 v47, v48, v49
	v_cvt_pk_bf16_f32 v48, v42, v43
	v_cvt_pk_bf16_f32 v49, v44, v45
	v_mov_b32_e32 v42, v46
	v_mov_b32_e32 v43, v47
	v_mov_b32_e32 v44, v48
	v_mov_b32_e32 v45, v49
	v_mov_b32_dpp v42, v38 row_ror:8 row_mask:0xf bank_mask:0xc
	v_mov_b32_dpp v43, v39 row_ror:8 row_mask:0xf bank_mask:0xc
	v_mov_b32_dpp v44, v40 row_ror:8 row_mask:0xf bank_mask:0xc
	v_mov_b32_dpp v45, v41 row_ror:8 row_mask:0xf bank_mask:0xc
	v_mov_b32_dpp v46, v38 row_ror:8 row_mask:0xf bank_mask:0x3
	v_mov_b32_dpp v47, v39 row_ror:8 row_mask:0xf bank_mask:0x3
	v_mov_b32_dpp v48, v40 row_ror:8 row_mask:0xf bank_mask:0x3
	v_mov_b32_dpp v49, v41 row_ror:8 row_mask:0xf bank_mask:0x3
	v_lshl_add_u64 v[142:143], v[152:153], 0, v[154:155]
	global_store_dwordx4 v[152:153], v[42:45], off
	global_store_dwordx4 v[142:143], v[46:49], off
	v_lshl_add_u64 v[152:153], v[152:153], 0, s[50:51]
	v_pk_mul_f32 v[18:19], v[18:19], v[172:173] op_sel_hi:[1,0]
	v_pk_mul_f32 v[20:21], v[20:21], v[172:173] op_sel_hi:[1,0]
	v_pk_mul_f32 v[22:23], v[22:23], v[172:173] op_sel_hi:[1,0]
	v_pk_mul_f32 v[24:25], v[24:25], v[172:173] op_sel_hi:[1,0]
	v_pk_mul_f32 v[26:27], v[26:27], v[172:173] op_sel_hi:[1,0]
	v_pk_mul_f32 v[28:29], v[28:29], v[172:173] op_sel_hi:[1,0]
	v_pk_mul_f32 v[30:31], v[30:31], v[172:173] op_sel_hi:[1,0]
	v_pk_mul_f32 v[32:33], v[32:33], v[172:173] op_sel_hi:[1,0]
	v_cvt_pk_bf16_f32 v22, v22, v23
	v_cvt_pk_bf16_f32 v23, v24, v25
	v_cvt_pk_bf16_f32 v24, v18, v19
	v_cvt_pk_bf16_f32 v25, v20, v21
	v_cvt_pk_bf16_f32 v30, v30, v31
	v_cvt_pk_bf16_f32 v31, v32, v33
	v_cvt_pk_bf16_f32 v32, v26, v27
	v_cvt_pk_bf16_f32 v33, v28, v29
	v_mov_b32_e32 v26, v30
	v_mov_b32_e32 v27, v31
	v_mov_b32_e32 v28, v32
	v_mov_b32_e32 v29, v33
	v_mov_b32_dpp v26, v22 row_ror:8 row_mask:0xf bank_mask:0xc
	v_mov_b32_dpp v27, v23 row_ror:8 row_mask:0xf bank_mask:0xc
	v_mov_b32_dpp v28, v24 row_ror:8 row_mask:0xf bank_mask:0xc
	v_mov_b32_dpp v29, v25 row_ror:8 row_mask:0xf bank_mask:0xc
	v_mov_b32_dpp v30, v22 row_ror:8 row_mask:0xf bank_mask:0x3
	v_mov_b32_dpp v31, v23 row_ror:8 row_mask:0xf bank_mask:0x3
	v_mov_b32_dpp v32, v24 row_ror:8 row_mask:0xf bank_mask:0x3
	v_mov_b32_dpp v33, v25 row_ror:8 row_mask:0xf bank_mask:0x3
	v_lshl_add_u64 v[142:143], v[152:153], 0, v[154:155]
	global_store_dwordx4 v[152:153], v[26:29], off
	global_store_dwordx4 v[142:143], v[30:33], off
	v_lshl_add_u64 v[152:153], v[152:153], 0, s[50:51]
	v_pk_mul_f32 v[2:3], v[2:3], v[174:175] op_sel_hi:[1,0]
	v_pk_mul_f32 v[4:5], v[4:5], v[174:175] op_sel_hi:[1,0]
	v_pk_mul_f32 v[6:7], v[6:7], v[174:175] op_sel_hi:[1,0]
	v_pk_mul_f32 v[8:9], v[8:9], v[174:175] op_sel_hi:[1,0]
	v_pk_mul_f32 v[10:11], v[10:11], v[174:175] op_sel_hi:[1,0]
	v_pk_mul_f32 v[12:13], v[12:13], v[174:175] op_sel_hi:[1,0]
	v_pk_mul_f32 v[14:15], v[14:15], v[174:175] op_sel_hi:[1,0]
	v_pk_mul_f32 v[16:17], v[16:17], v[174:175] op_sel_hi:[1,0]
	v_cvt_pk_bf16_f32 v6, v6, v7
	v_cvt_pk_bf16_f32 v7, v8, v9
	v_cvt_pk_bf16_f32 v8, v2, v3
	v_cvt_pk_bf16_f32 v9, v4, v5
	v_cvt_pk_bf16_f32 v14, v14, v15
	v_cvt_pk_bf16_f32 v15, v16, v17
	v_cvt_pk_bf16_f32 v16, v10, v11
	v_cvt_pk_bf16_f32 v17, v12, v13
	v_mov_b32_e32 v10, v14
	v_mov_b32_e32 v11, v15
	v_mov_b32_e32 v12, v16
	v_mov_b32_e32 v13, v17
	v_mov_b32_dpp v10, v6 row_ror:8 row_mask:0xf bank_mask:0xc
	v_mov_b32_dpp v11, v7 row_ror:8 row_mask:0xf bank_mask:0xc
	v_mov_b32_dpp v12, v8 row_ror:8 row_mask:0xf bank_mask:0xc
	v_mov_b32_dpp v13, v9 row_ror:8 row_mask:0xf bank_mask:0xc
	v_mov_b32_dpp v14, v6 row_ror:8 row_mask:0xf bank_mask:0x3
	v_mov_b32_dpp v15, v7 row_ror:8 row_mask:0xf bank_mask:0x3
	v_mov_b32_dpp v16, v8 row_ror:8 row_mask:0xf bank_mask:0x3
	v_mov_b32_dpp v17, v9 row_ror:8 row_mask:0xf bank_mask:0x3
	v_lshl_add_u64 v[142:143], v[152:153], 0, v[154:155]
	global_store_dwordx4 v[152:153], v[10:13], off
	global_store_dwordx4 v[142:143], v[14:17], off
	s_andn2_b64 vcc, exec, s[40:41]
	s_mov_b64 s[10:11], -1
	s_cbranch_vccnz .LBB0_555
	s_andn2_b64 vcc, exec, s[8:9]
	s_cbranch_vccnz .LBB0_554
	s_barrier
	s_branch .LBB0_554
